# DeltaNet C1 (16x16 block inverse) load phase: removed 8 serialized WAW-only lgkmcnt(0) between overlapping ds_read_b128 (in-order LDS return), counted waits instead
# speedup vs baseline: 1.0103x; 1.0028x over previous
.LBB0_673:
	s_andn2_b64 vcc, exec, s[0:1]
	v_lshl_add_u32 v80, v73, 6, v64
	s_cbranch_vccnz .LBB0_677
	ds_write_b32 v80, v60
	v_cvt_pk_bf16_f32 v60, v61, s0
	v_add_u32_e32 v61, 0x19200, v62
	ds_write_b16 v61, v60
	s_waitcnt lgkmcnt(0)
	s_and_saveexec_b64 s[0:1], s[10:11]
	s_cbranch_execz .LBB0_676
	v_mov_b32_e32 v83, s42
	ds_read_b128 v[60:63], v83 offset:64
	ds_read_b128 v[62:65], v83 offset:128
	ds_read_b128 v[64:67], v83 offset:192
	ds_read_b128 v[84:87], v83 offset:256
	ds_read_b128 v[88:91], v83 offset:320
	ds_read_b128 v[92:95], v83 offset:336
	ds_read_b128 v[94:97], v83 offset:384
	ds_read_b128 v[98:101], v83 offset:400
	ds_read_b128 v[100:103], v83 offset:448
	ds_read_b128 v[156:159], v83 offset:464
	ds_read_b128 v[160:163], v83 offset:512
	ds_read_b128 v[164:167], v83 offset:528
	ds_read_b128 v[168:171], v83 offset:576
	ds_read_b128 v[172:175], v83 offset:592
	ds_read_b128 v[176:179], v83 offset:608
	ds_read_b128 v[178:181], v83 offset:640
	ds_read_b128 v[182:185], v83 offset:656
	ds_read_b128 v[186:189], v83 offset:672
	s_waitcnt lgkmcnt(15)
	v_fma_f32 v60, -v125, v60, v127
	s_waitcnt lgkmcnt(15)
	v_fma_f32 v62, -v125, v62, v128
	ds_read_b128 v[188:191], v83 offset:704
	ds_read_b128 v[192:195], v83 offset:720
	ds_read_b128 v[196:199], v83 offset:736
	ds_read_b128 v[200:203], v83 offset:768
	ds_read_b128 v[204:207], v83 offset:784
	ds_read_b128 v[208:211], v83 offset:800
	ds_read_b128 v[212:215], v83 offset:832
	ds_read_b128 v[216:219], v83 offset:848
	ds_read_b128 v[220:223], v83 offset:864
	ds_read_b128 v[226:229], v83 offset:880
	s_waitcnt lgkmcnt(15)
	v_fma_f32 v62, -v63, v60, v62
	ds_read_b128 v[228:231], v83 offset:896
	ds_read_b128 v[232:235], v83 offset:912
	ds_read_b128 v[236:239], v83 offset:928
	ds_read_b128 v[240:243], v83 offset:944
	s_waitcnt lgkmcnt(15)
	v_add_u32_e32 v61, s62, v123
	s_waitcnt lgkmcnt(15)
	v_cvt_pk_bf16_f32 v63, v62, s0
	ds_read_b128 v[242:245], v83 offset:960
	ds_read_b128 v[246:249], v83 offset:976
	ds_read_b128 v[250:253], v83 offset:992
	ds_read_b128 v[140:143], v83 offset:1008
	s_waitcnt lgkmcnt(4)
	ds_write_b16 v61, v63 offset:80
	v_fma_f32 v63, -v125, v64, v129
	v_fma_f32 v63, -v65, v60, v63
	v_fma_f32 v63, -v66, v62, v63
	v_cvt_pk_bf16_f32 v64, v63, s0
	ds_write_b16 v61, v64 offset:120
	v_fma_f32 v64, -v125, v84, v130
	v_fma_f32 v64, -v60, v85, v64
	v_fma_f32 v64, -v86, v62, v64
	v_fma_f32 v64, -v87, v63, v64
	v_cvt_pk_bf16_f32 v65, v64, s0
	ds_write_b16 v61, v65 offset:160
	v_fma_f32 v65, -v125, v88, v131
	v_fma_f32 v65, -v60, v89, v65
	v_fma_f32 v65, -v90, v62, v65
	v_fma_f32 v65, -v91, v63, v65
	v_fma_f32 v65, -v92, v64, v65
	v_cvt_pk_bf16_f32 v66, v65, s0
	ds_write_b16 v61, v66 offset:200
	v_fma_f32 v66, -v125, v94, v132
	v_fma_f32 v66, -v60, v95, v66
	v_fma_f32 v66, -v62, v96, v66
	v_fma_f32 v66, -v97, v63, v66
	v_fma_f32 v66, -v98, v64, v66
	v_cvt_pk_bf16_f32 v67, v60, s0
	v_fma_f32 v66, -v99, v65, v66
	ds_write_b16 v61, v67 offset:40
	v_cvt_pk_bf16_f32 v67, v66, s0
	ds_write_b16 v61, v67 offset:240
	v_fma_f32 v67, -v125, v100, v133
	v_fma_f32 v67, -v60, v101, v67
	v_fma_f32 v67, -v62, v102, v67
	v_fma_f32 v67, -v63, v103, v67
	v_fma_f32 v67, -v64, v156, v67
	v_fma_f32 v67, -v157, v65, v67
	v_fma_f32 v67, -v158, v66, v67
	v_cvt_pk_bf16_f32 v83, v67, s0
	ds_write_b16 v61, v83 offset:280
	v_fma_f32 v83, -v125, v160, v134
	v_fma_f32 v83, -v60, v161, v83
	v_fma_f32 v83, -v62, v162, v83
	v_fma_f32 v83, -v63, v163, v83
	v_fma_f32 v83, -v64, v164, v83
	v_fma_f32 v83, -v65, v165, v83
	v_fma_f32 v83, -v166, v66, v83
	v_fma_f32 v83, -v167, v67, v83
	v_cvt_pk_bf16_f32 v84, v83, s0
	ds_write_b16 v61, v84 offset:320
	v_fma_f32 v84, -v125, v168, v135
	v_fma_f32 v84, -v60, v169, v84
	v_fma_f32 v84, -v62, v170, v84
	v_fma_f32 v84, -v63, v171, v84
	v_fma_f32 v84, -v64, v172, v84
	v_fma_f32 v84, -v65, v173, v84
	v_fma_f32 v84, -v174, v66, v84
	v_fma_f32 v84, -v175, v67, v84
	v_fma_f32 v84, -v176, v83, v84
	v_cvt_pk_bf16_f32 v85, v84, s0
	ds_write_b16 v61, v85 offset:360
	v_fma_f32 v85, -v125, v178, v136
	v_fma_f32 v85, -v60, v179, v85
	v_fma_f32 v85, -v62, v180, v85
	v_fma_f32 v85, -v63, v181, v85
	v_fma_f32 v85, -v64, v182, v85
	v_fma_f32 v85, -v65, v183, v85
	v_fma_f32 v85, -v66, v184, v85
	v_fma_f32 v85, -v185, v67, v85
	v_fma_f32 v85, -v186, v83, v85
	v_fma_f32 v85, -v187, v84, v85
	v_cvt_pk_bf16_f32 v86, v85, s0
	ds_write_b16 v61, v86 offset:400
	v_fma_f32 v86, -v125, v188, v138
	v_fma_f32 v86, -v60, v189, v86
	v_fma_f32 v86, -v62, v190, v86
	v_fma_f32 v86, -v63, v191, v86
	v_fma_f32 v86, -v64, v192, v86
	v_fma_f32 v86, -v65, v193, v86
	v_fma_f32 v86, -v66, v194, v86
	v_fma_f32 v86, -v67, v195, v86
	v_fma_f32 v86, -v83, v196, v86
	v_fma_f32 v86, -v197, v84, v86
	v_fma_f32 v86, -v198, v85, v86
	v_cvt_pk_bf16_f32 v87, v86, s0
	ds_write_b16 v61, v87 offset:440
	v_fma_f32 v87, -v125, v200, v139
	v_fma_f32 v87, -v60, v201, v87
	v_fma_f32 v87, -v62, v202, v87
	v_fma_f32 v87, -v63, v203, v87
	v_fma_f32 v87, -v64, v204, v87
	v_fma_f32 v87, -v65, v205, v87
	v_fma_f32 v87, -v66, v206, v87
	v_fma_f32 v87, -v67, v207, v87
	v_fma_f32 v87, -v83, v208, v87
	v_fma_f32 v87, -v84, v209, v87
	v_fma_f32 v87, -v210, v85, v87
	v_fma_f32 v87, -v211, v86, v87
	v_cvt_pk_bf16_f32 v88, v87, s0
	ds_write_b16 v61, v88 offset:480
	v_fma_f32 v88, -v125, v212, v152
	v_fma_f32 v88, -v60, v213, v88
	v_fma_f32 v88, -v62, v214, v88
	v_fma_f32 v88, -v63, v215, v88
	v_fma_f32 v88, -v64, v216, v88
	v_fma_f32 v88, -v65, v217, v88
	v_fma_f32 v88, -v66, v218, v88
	v_fma_f32 v88, -v67, v219, v88
	v_fma_f32 v88, -v83, v220, v88
	v_fma_f32 v88, -v84, v221, v88
	v_fma_f32 v88, -v222, v85, v88
	v_fma_f32 v88, -v223, v86, v88
	v_fma_f32 v88, -v226, v87, v88
	v_cvt_pk_bf16_f32 v89, v88, s0
	ds_write_b16 v61, v89 offset:520
	v_fma_f32 v89, -v125, v228, v153
	v_fma_f32 v89, -v60, v229, v89
	v_fma_f32 v89, -v62, v230, v89
	v_fma_f32 v89, -v63, v231, v89
	v_fma_f32 v89, -v64, v232, v89
	v_fma_f32 v89, -v65, v233, v89
	v_fma_f32 v89, -v66, v234, v89
	v_fma_f32 v89, -v67, v235, v89
	v_fma_f32 v89, -v83, v236, v89
	v_fma_f32 v89, -v84, v237, v89
	v_fma_f32 v89, -v85, v238, v89
	v_fma_f32 v89, -v239, v86, v89
	v_fma_f32 v89, -v240, v87, v89
	v_fma_f32 v89, -v241, v88, v89
	v_cvt_pk_bf16_f32 v90, v89, s0
	ds_write_b16 v61, v90 offset:560
	s_waitcnt lgkmcnt(14)
	v_fma_f32 v90, -v125, v242, v154
	v_fma_f32 v60, -v60, v243, v90
	v_fma_f32 v60, -v62, v244, v60
	v_fma_f32 v60, -v63, v245, v60
	v_fma_f32 v60, -v64, v246, v60
	v_fma_f32 v60, -v65, v247, v60
	v_fma_f32 v60, -v66, v248, v60
	v_fma_f32 v60, -v67, v249, v60
	v_fma_f32 v60, -v83, v250, v60
	v_fma_f32 v60, -v84, v251, v60
	v_fma_f32 v60, -v85, v252, v60
	v_fma_f32 v60, -v86, v253, v60
	v_fma_f32 v60, -v87, v140, v60
	v_fma_f32 v60, -v141, v88, v60
	v_fma_f32 v60, -v142, v89, v60
	v_cvt_pk_bf16_f32 v60, v60, s0
	ds_write_b16 v61, v126
	ds_write_b16 v61, v60 offset:600

.LBB0_701:
	s_andn2_b64 vcc, exec, s[0:1]
	s_cbranch_vccnz .LBB0_705
	v_cvt_pk_bf16_f32 v1, v1, s0
	v_add_u32_e32 v0, 0x19200, v0
	ds_write_b32 v80, v60
	ds_write_b16 v0, v1
	s_waitcnt lgkmcnt(0)
	s_and_saveexec_b64 s[0:1], s[10:11]
	s_cbranch_execz .LBB0_704
	v_mov_b32_e32 v0, s42
	ds_read_b128 v[60:63], v0 offset:64
	ds_read_b128 v[62:65], v0 offset:128
	ds_read_b128 v[64:67], v0 offset:192
	ds_read_b128 v[68:71], v0 offset:256
	ds_read_b128 v[72:75], v0 offset:320
	ds_read_b128 v[76:79], v0 offset:336
	ds_read_b128 v[78:81], v0 offset:384
	ds_read_b128 v[82:85], v0 offset:400
	ds_read_b128 v[84:87], v0 offset:448
	ds_read_b128 v[88:91], v0 offset:464
	ds_read_b128 v[92:95], v0 offset:512
	ds_read_b128 v[96:99], v0 offset:528
	ds_read_b128 v[100:103], v0 offset:576
	ds_read_b128 v[140:143], v0 offset:592
	ds_read_b128 v[156:159], v0 offset:608
	ds_read_b128 v[158:161], v0 offset:640
	ds_read_b128 v[162:165], v0 offset:656
	ds_read_b128 v[166:169], v0 offset:672
	ds_read_b128 v[168:171], v0 offset:704
	ds_read_b128 v[172:175], v0 offset:720
	ds_read_b128 v[176:179], v0 offset:736
	ds_read_b128 v[180:183], v0 offset:768
	ds_read_b128 v[184:187], v0 offset:784
	ds_read_b128 v[188:191], v0 offset:800
	ds_read_b128 v[192:195], v0 offset:832
	ds_read_b128 v[196:199], v0 offset:848
	ds_read_b128 v[200:203], v0 offset:864
	ds_read_b128 v[204:207], v0 offset:880
	ds_read_b128 v[206:209], v0 offset:896
	ds_read_b128 v[210:213], v0 offset:912
	ds_read_b128 v[214:217], v0 offset:928
	ds_read_b128 v[218:221], v0 offset:944
	s_waitcnt lgkmcnt(15)
	v_fma_f32 v1, -v125, v60, v127
	ds_read_b128 v[220:223], v0 offset:960
	ds_read_b128 v[226:229], v0 offset:976
	ds_read_b128 v[230:233], v0 offset:992
	ds_read_b128 v[234:237], v0 offset:1008
	s_waitcnt lgkmcnt(4)
	v_add_u32_e32 v0, s62, v123
	v_cvt_pk_bf16_f32 v3, v1, s0
	ds_write_b16 v0, v3 offset:40
	v_fma_f32 v3, -v125, v62, v128
	v_fma_f32 v3, -v63, v1, v3
	v_cvt_pk_bf16_f32 v60, v3, s0
	ds_write_b16 v0, v60 offset:80
	v_fma_f32 v60, -v125, v64, v129
	v_fma_f32 v60, -v65, v1, v60
	v_fma_f32 v60, -v66, v3, v60
	v_cvt_pk_bf16_f32 v61, v60, s0
	ds_write_b16 v0, v61 offset:120
	v_fma_f32 v61, -v125, v68, v130
	v_fma_f32 v61, -v1, v69, v61
	v_fma_f32 v61, -v70, v3, v61
	v_fma_f32 v61, -v71, v60, v61
	v_cvt_pk_bf16_f32 v62, v61, s0
	ds_write_b16 v0, v62 offset:160
	v_fma_f32 v62, -v125, v72, v131
	v_fma_f32 v62, -v1, v73, v62
	v_fma_f32 v62, -v74, v3, v62
	v_fma_f32 v62, -v75, v60, v62
	v_fma_f32 v62, -v76, v61, v62
	v_cvt_pk_bf16_f32 v63, v62, s0
	ds_write_b16 v0, v63 offset:200
	v_fma_f32 v63, -v125, v78, v132
	v_fma_f32 v63, -v1, v79, v63
	v_fma_f32 v63, -v3, v80, v63
	v_fma_f32 v63, -v81, v60, v63
	v_fma_f32 v63, -v82, v61, v63
	v_fma_f32 v63, -v83, v62, v63
	v_cvt_pk_bf16_f32 v64, v63, s0
	ds_write_b16 v0, v64 offset:240
	v_fma_f32 v64, -v125, v84, v133
	v_fma_f32 v64, -v1, v85, v64
	v_fma_f32 v64, -v3, v86, v64
	v_fma_f32 v64, -v60, v87, v64
	v_fma_f32 v64, -v61, v88, v64
	v_fma_f32 v64, -v89, v62, v64
	v_fma_f32 v64, -v90, v63, v64
	v_cvt_pk_bf16_f32 v65, v64, s0
	ds_write_b16 v0, v65 offset:280
	v_fma_f32 v65, -v125, v92, v134
	v_fma_f32 v65, -v1, v93, v65
	v_fma_f32 v65, -v3, v94, v65
	v_fma_f32 v65, -v60, v95, v65
	v_fma_f32 v65, -v61, v96, v65
	v_fma_f32 v65, -v62, v97, v65
	v_fma_f32 v65, -v98, v63, v65
	v_fma_f32 v65, -v99, v64, v65
	v_cvt_pk_bf16_f32 v66, v65, s0
	ds_write_b16 v0, v66 offset:320
	v_fma_f32 v66, -v125, v100, v135
	v_fma_f32 v66, -v1, v101, v66
	v_fma_f32 v66, -v3, v102, v66
	v_fma_f32 v66, -v60, v103, v66
	v_fma_f32 v66, -v61, v140, v66
	v_fma_f32 v66, -v62, v141, v66
	v_fma_f32 v66, -v142, v63, v66
	v_fma_f32 v66, -v143, v64, v66
	v_fma_f32 v66, -v156, v65, v66
	v_cvt_pk_bf16_f32 v67, v66, s0
	ds_write_b16 v0, v67 offset:360
	v_fma_f32 v67, -v125, v158, v136
	v_fma_f32 v67, -v1, v159, v67
	v_fma_f32 v67, -v3, v160, v67
	v_fma_f32 v67, -v60, v161, v67
	v_fma_f32 v67, -v61, v162, v67
	v_fma_f32 v67, -v62, v163, v67
	v_fma_f32 v67, -v63, v164, v67
	v_fma_f32 v67, -v165, v64, v67
	v_fma_f32 v67, -v166, v65, v67
	v_fma_f32 v67, -v167, v66, v67
	v_cvt_pk_bf16_f32 v68, v67, s0
	ds_write_b16 v0, v68 offset:400
	v_fma_f32 v68, -v125, v168, v138
	v_fma_f32 v68, -v1, v169, v68
	v_fma_f32 v68, -v3, v170, v68
	v_fma_f32 v68, -v60, v171, v68
	v_fma_f32 v68, -v61, v172, v68
	v_fma_f32 v68, -v62, v173, v68
	v_fma_f32 v68, -v63, v174, v68
	v_fma_f32 v68, -v64, v175, v68
	v_fma_f32 v68, -v65, v176, v68
	v_fma_f32 v68, -v177, v66, v68
	v_fma_f32 v68, -v178, v67, v68
	v_cvt_pk_bf16_f32 v69, v68, s0
	ds_write_b16 v0, v69 offset:440
	v_fma_f32 v69, -v125, v180, v139
	v_fma_f32 v69, -v1, v181, v69
	v_fma_f32 v69, -v3, v182, v69
	v_fma_f32 v69, -v60, v183, v69
	v_fma_f32 v69, -v61, v184, v69
	v_fma_f32 v69, -v62, v185, v69
	v_fma_f32 v69, -v63, v186, v69
	v_fma_f32 v69, -v64, v187, v69
	v_fma_f32 v69, -v65, v188, v69
	v_fma_f32 v69, -v66, v189, v69
	v_fma_f32 v69, -v190, v67, v69
	v_fma_f32 v69, -v191, v68, v69
	v_cvt_pk_bf16_f32 v70, v69, s0
	ds_write_b16 v0, v70 offset:480
	v_fma_f32 v70, -v125, v192, v152
	v_fma_f32 v70, -v1, v193, v70
	v_fma_f32 v70, -v3, v194, v70
	v_fma_f32 v70, -v60, v195, v70
	v_fma_f32 v70, -v61, v196, v70
	v_fma_f32 v70, -v62, v197, v70
	v_fma_f32 v70, -v63, v198, v70
	v_fma_f32 v70, -v64, v199, v70
	v_fma_f32 v70, -v65, v200, v70
	v_fma_f32 v70, -v66, v201, v70
	v_fma_f32 v70, -v202, v67, v70
	v_fma_f32 v70, -v203, v68, v70
	v_fma_f32 v70, -v204, v69, v70
	v_cvt_pk_bf16_f32 v71, v70, s0
	ds_write_b16 v0, v71 offset:520
	v_fma_f32 v71, -v125, v206, v153
	v_fma_f32 v71, -v1, v207, v71
	v_fma_f32 v71, -v3, v208, v71
	v_fma_f32 v71, -v60, v209, v71
	v_fma_f32 v71, -v61, v210, v71
	v_fma_f32 v71, -v62, v211, v71
	v_fma_f32 v71, -v63, v212, v71
	v_fma_f32 v71, -v64, v213, v71
	v_fma_f32 v71, -v65, v214, v71
	v_fma_f32 v71, -v66, v215, v71
	v_fma_f32 v71, -v67, v216, v71
	v_fma_f32 v71, -v217, v68, v71
	v_fma_f32 v71, -v218, v69, v71
	v_fma_f32 v71, -v219, v70, v71
	v_cvt_pk_bf16_f32 v72, v71, s0
	ds_write_b16 v0, v72 offset:560
	s_waitcnt lgkmcnt(14)
	v_fma_f32 v72, -v125, v220, v154
	v_fma_f32 v1, -v1, v221, v72
	v_fma_f32 v1, -v3, v222, v1
	v_fma_f32 v1, -v60, v223, v1
	v_fma_f32 v1, -v61, v226, v1
	v_fma_f32 v1, -v62, v227, v1
	v_fma_f32 v1, -v63, v228, v1
	v_fma_f32 v1, -v64, v229, v1
	v_fma_f32 v1, -v65, v230, v1
	v_fma_f32 v1, -v66, v231, v1
	v_fma_f32 v1, -v67, v232, v1
	v_fma_f32 v1, -v68, v233, v1
	v_fma_f32 v1, -v69, v234, v1
	v_fma_f32 v1, -v235, v70, v1
	v_fma_f32 v1, -v236, v71, v1
	v_cvt_pk_bf16_f32 v1, v1, s0
	ds_write_b16 v0, v126
	ds_write_b16 v0, v1 offset:600
